# m1 transposed K-tile LDS stores: XOR swizzle removes the 8-way bank conflict (writer and MFMA B-operand reads agree)
# speedup vs baseline: 1.0077x; 1.0077x over previous
.LBB0_292:
	s_lshl_b32 s91, s29, 8
	s_add_u32 s91, s91, 0x1a000
	v_add_u32_e32 v191, s91, v208
	ds_read_b128 v[72:75], v191 offset:18432
	ds_read_b128 v[76:79], v191 offset:18448
	ds_read_b128 v[84:87], v191 offset:2048
	ds_read_b128 v[88:91], v191 offset:2064
	ds_read_b128 v[96:99], v191 offset:6144
	ds_read_b128 v[100:103], v191 offset:6160
	ds_read_b128 v[108:111], v191 offset:10240
	ds_read_b128 v[112:115], v191 offset:10256
	ds_read_b128 v[120:123], v191 offset:14336
	ds_read_b128 v[124:127], v191 offset:14352
	v_lshrrev_b32_e32 v8, 3, v15
	v_and_b32_e32 v16, 7, v15
	v_lshlrev_b32_e32 v16, 3, v16
	v_mul_u32_u24_e32 v24, 0x90, v8
	v_lshl_add_u32 v24, v16, 1, v24
	s_waitcnt vmcnt(0)
	ds_write_b128 v24, v[44:47] offset:9216
	ds_write_b128 v24, v[48:51] offset:18432
	v_cmp_gt_i32_e32 vcc, s66, v15
	s_and_saveexec_b64 s[4:5], vcc
	v_cmp_gt_u32_e32 vcc, 8, v15
	s_nop 1
	v_cndmask_b32_e32 v2, 0, v205, vcc
	v_mov_b32_e32 v3, v2
	v_mov_b32_e32 v4, v2
	v_mov_b32_e32 v5, v2
	ds_write_b128 v24, v[2:5] offset:27648
	s_or_b64 exec, exec, s[4:5]
	s_waitcnt lgkmcnt(0)
	v_mov_b32_e32 v4, v72
	v_mov_b32_e32 v5, v73
	v_mov_b32_e32 v6, v74
	v_mov_b32_e32 v7, v75
	v_mov_b32_e32 v0, v76
	v_mov_b32_e32 v1, v77
	v_mov_b32_e32 v2, v78
	v_mov_b32_e32 v3, v79
	s_and_saveexec_b64 s[4:5], s[46:47]
	v_lshlrev_b32_e32 v32, 16, v80
	v_and_b32_e32 v33, 0xffff0000, v80
	v_pk_fma_f32 v[4:5], v[84:85], v[32:33], v[4:5]
	v_lshlrev_b32_e32 v34, 16, v81
	v_and_b32_e32 v35, 0xffff0000, v81
	v_pk_fma_f32 v[6:7], v[86:87], v[34:35], v[6:7]
	v_lshlrev_b32_e32 v32, 16, v82
	v_and_b32_e32 v33, 0xffff0000, v82
	v_pk_fma_f32 v[0:1], v[88:89], v[32:33], v[0:1]
	v_lshlrev_b32_e32 v34, 16, v83
	v_and_b32_e32 v35, 0xffff0000, v83
	v_pk_fma_f32 v[2:3], v[90:91], v[34:35], v[2:3]
	s_or_b64 exec, exec, s[4:5]
	s_and_saveexec_b64 s[4:5], s[48:49]
	v_lshlrev_b32_e32 v32, 16, v92
	v_and_b32_e32 v33, 0xffff0000, v92
	v_pk_fma_f32 v[4:5], v[96:97], v[32:33], v[4:5]
	v_lshlrev_b32_e32 v34, 16, v93
	v_and_b32_e32 v35, 0xffff0000, v93
	v_pk_fma_f32 v[6:7], v[98:99], v[34:35], v[6:7]
	v_lshlrev_b32_e32 v32, 16, v94
	v_and_b32_e32 v33, 0xffff0000, v94
	v_pk_fma_f32 v[0:1], v[100:101], v[32:33], v[0:1]
	v_lshlrev_b32_e32 v34, 16, v95
	v_and_b32_e32 v35, 0xffff0000, v95
	v_pk_fma_f32 v[2:3], v[102:103], v[34:35], v[2:3]
	s_or_b64 exec, exec, s[4:5]
	s_and_saveexec_b64 s[4:5], s[50:51]
	v_lshlrev_b32_e32 v32, 16, v104
	v_and_b32_e32 v33, 0xffff0000, v104
	v_pk_fma_f32 v[4:5], v[108:109], v[32:33], v[4:5]
	v_lshlrev_b32_e32 v34, 16, v105
	v_and_b32_e32 v35, 0xffff0000, v105
	v_pk_fma_f32 v[6:7], v[110:111], v[34:35], v[6:7]
	v_lshlrev_b32_e32 v32, 16, v106
	v_and_b32_e32 v33, 0xffff0000, v106
	v_pk_fma_f32 v[0:1], v[112:113], v[32:33], v[0:1]
	v_lshlrev_b32_e32 v34, 16, v107
	v_and_b32_e32 v35, 0xffff0000, v107
	v_pk_fma_f32 v[2:3], v[114:115], v[34:35], v[2:3]
	s_or_b64 exec, exec, s[4:5]
	v_lshlrev_b32_e32 v32, 16, v116
	v_and_b32_e32 v33, 0xffff0000, v116
	v_pk_fma_f32 v[4:5], v[120:121], v[32:33], v[4:5]
	v_lshlrev_b32_e32 v34, 16, v117
	v_and_b32_e32 v35, 0xffff0000, v117
	v_pk_fma_f32 v[6:7], v[122:123], v[34:35], v[6:7]
	v_lshlrev_b32_e32 v32, 16, v118
	v_and_b32_e32 v33, 0xffff0000, v118
	v_pk_fma_f32 v[0:1], v[124:125], v[32:33], v[0:1]
	v_lshlrev_b32_e32 v34, 16, v119
	v_and_b32_e32 v35, 0xffff0000, v119
	v_pk_fma_f32 v[2:3], v[126:127], v[34:35], v[2:3]
	s_waitcnt vmcnt(0)
	v_mul_f32_e32 v11, 0xbfb8aa3b, v4
	v_exp_f32_e32 v11, v11
	s_waitcnt lgkmcnt(0)
	s_barrier
	v_add_f32_e32 v11, 1.0, v11
	v_rcp_f32_e32 v11, v11
	s_movk_i32 s19, 0x7fff
	v_and_b32_e32 v9, 15, v15
	s_lshr_b32 s4, s27, 2
	v_mul_f32_e32 v4, v4, v11
	v_mul_f32_e32 v11, 0xbfb8aa3b, v5
	v_exp_f32_e32 v11, v11
	v_lshrrev_b32_e32 v10, 4, v14
	v_lshlrev_b32_e32 v24, 2, v10
	v_add_f32_e32 v11, 1.0, v11
	v_rcp_f32_e32 v11, v11
	s_nop 0
	v_mul_f32_e32 v5, v5, v11
	v_mul_f32_e32 v11, 0xbfb8aa3b, v6
	v_exp_f32_e32 v11, v11
	s_nop 0
	v_add_f32_e32 v11, 1.0, v11
	v_rcp_f32_e32 v11, v11
	s_nop 0
	v_mul_f32_e32 v6, v6, v11
	v_mul_f32_e32 v11, 0xbfb8aa3b, v7
	v_exp_f32_e32 v11, v11
	s_nop 0
	v_add_f32_e32 v11, 1.0, v11
	v_rcp_f32_e32 v11, v11
	s_nop 0
	v_mul_f32_e32 v7, v7, v11
	v_mul_f32_e32 v11, 0xbfb8aa3b, v0
	v_exp_f32_e32 v11, v11
	s_nop 0
	v_add_f32_e32 v11, 1.0, v11
	v_rcp_f32_e32 v11, v11
	s_nop 0
	v_mul_f32_e32 v0, v0, v11
	v_mul_f32_e32 v11, 0xbfb8aa3b, v1
	v_exp_f32_e32 v11, v11
	s_nop 0
	v_add_f32_e32 v11, 1.0, v11
	v_rcp_f32_e32 v11, v11
	s_nop 0
	v_mul_f32_e32 v1, v1, v11
	v_mul_f32_e32 v11, 0xbfb8aa3b, v2
	v_exp_f32_e32 v11, v11
	s_nop 0
	v_add_f32_e32 v11, 1.0, v11
	v_rcp_f32_e32 v11, v11
	s_nop 0
	v_mul_f32_e32 v2, v2, v11
	v_mul_f32_e32 v11, 0xbfb8aa3b, v3
	v_exp_f32_e32 v11, v11
	s_nop 0
	v_add_f32_e32 v11, 1.0, v11
	v_rcp_f32_e32 v11, v11
	s_nop 0
	v_mul_f32_e32 v3, v3, v11
	v_lshl_add_u32 v11, v8, 2, 0
	ds_read_b32 v12, v11 offset:29952
	v_lshlrev_b32_e32 v8, 1, v8
	v_sub_u32_e32 v8, v11, v8
	v_lshlrev_b32_e32 v13, 1, v16
	v_xor_b32_e32 v8, v8, v13
	v_mad_u32_u24 v8, v16, s84, v8
	s_waitcnt lgkmcnt(0)
	v_mul_f32_e32 v4, v12, v4
	v_bfe_u32 v11, v4, 16, 1
	v_add3_u32 v4, v4, v11, s19
	ds_write_b16_d16_hi v8, v4
	v_mul_f32_e32 v4, v12, v5
	v_bfe_u32 v5, v4, 16, 1
	v_add3_u32 v4, v4, v5, s19
	ds_write_b16_d16_hi v8, v4 offset:144
	v_mul_f32_e32 v4, v12, v6
	v_bfe_u32 v5, v4, 16, 1
	v_add3_u32 v4, v4, v5, s19
	ds_write_b16_d16_hi v8, v4 offset:288
	v_mul_f32_e32 v4, v12, v7
	v_bfe_u32 v5, v4, 16, 1
	v_add3_u32 v4, v4, v5, s19
	v_mul_f32_e32 v0, v12, v0
	ds_write_b16_d16_hi v8, v4 offset:432
	v_bfe_u32 v4, v0, 16, 1
	v_add3_u32 v0, v0, v4, s19
	ds_write_b16_d16_hi v8, v0 offset:576
	v_mul_f32_e32 v0, v12, v1
	v_bfe_u32 v1, v0, 16, 1
	v_add3_u32 v0, v0, v1, s19
	ds_write_b16_d16_hi v8, v0 offset:720
	v_mul_f32_e32 v0, v12, v2
	v_bfe_u32 v1, v0, 16, 1
	v_add3_u32 v0, v0, v1, s19
	ds_write_b16_d16_hi v8, v0 offset:864
	v_mul_f32_e32 v0, v12, v3
	v_bfe_u32 v1, v0, 16, 1
	v_add3_u32 v0, v0, v1, s19
	v_and_or_b32 v11, s4, 48, v9
	s_ashr_i32 s4, s27, 2
	ds_write_b16_d16_hi v8, v0 offset:1008
	v_and_b32_e32 v0, 48, v14
	s_andn2_b32 s4, s4, 63
	v_add_u32_e32 v8, 0, v0
	v_or_b32_e32 v0, s4, v9
	v_mad_u64_u32 v[12:13], s[6:7], v0, s84, v[8:9]
	s_waitcnt lgkmcnt(0)
	s_barrier
	v_lshrrev_b32_e32 v32, 3, v11
	v_and_b32_e32 v32, 7, v32
	v_lshlrev_b32_e32 v32, 4, v32
	v_xor_b32_e32 v32, v8, v32
	v_mad_u32_u24 v15, v11, s84, v32
	v_xor_b32_e32 v32, 64, v32
	v_mad_u32_u24 v33, v11, s84, v32
	ds_read_b128 v[4:7], v12 offset:9216
	ds_read_b128 v[0:3], v15
	s_waitcnt lgkmcnt(0)
	v_mfma_f32_16x16x32_bf16 v[16:19], v[4:7], v[0:3], 0
	ds_read_b128 v[20:23], v12 offset:9280
	ds_read_b128 v[4:7], v33
	v_or_b32_e32 v12, s4, v24
	v_lshl_or_b32 v12, v12, 6, v11
	s_waitcnt lgkmcnt(0)
	v_mfma_f32_16x16x32_bf16 v[16:19], v[20:23], v[4:7], v[16:19]
	s_or_b32 s5, s4, 16
	s_nop 6
	v_bfe_u32 v13, v16, 16, 1
	v_add3_u32 v15, v16, v13, s19
	v_ashrrev_i32_e32 v13, 31, v12
	v_lshl_add_u64 v[12:13], v[12:13], 1, s[16:17]
	global_store_short_d16_hi v[12:13], v15, off
	v_bfe_u32 v15, v17, 16, 1
	v_add3_u32 v15, v17, v15, s19
	global_store_short_d16_hi v[12:13], v15, off offset:128
	v_bfe_u32 v15, v18, 16, 1
	v_add3_u32 v15, v18, v15, s19
	global_store_short_d16_hi v[12:13], v15, off offset:256
	v_bfe_u32 v15, v19, 16, 1
	v_add3_u32 v15, v19, v15, s19
	global_store_short_d16_hi v[12:13], v15, off offset:384
	v_or_b32_e32 v12, s5, v9
	v_mad_u64_u32 v[12:13], s[6:7], v12, s84, v[8:9]
	ds_read_b128 v[16:19], v12 offset:9216
	ds_read_b128 v[20:23], v12 offset:9280
	s_waitcnt lgkmcnt(1)
	v_mfma_f32_16x16x32_bf16 v[16:19], v[16:19], v[0:3], 0
	v_or_b32_e32 v12, s5, v24
	v_lshl_or_b32 v12, v12, 6, v11
	s_or_b32 s5, s4, 32
	s_waitcnt lgkmcnt(0)
	v_mfma_f32_16x16x32_bf16 v[16:19], v[20:23], v[4:7], v[16:19]
	s_nop 7
	v_bfe_u32 v13, v16, 16, 1
	v_add3_u32 v15, v16, v13, s19
	v_ashrrev_i32_e32 v13, 31, v12
	v_lshl_add_u64 v[12:13], v[12:13], 1, s[16:17]
	global_store_short_d16_hi v[12:13], v15, off
	v_bfe_u32 v15, v17, 16, 1
	v_add3_u32 v15, v17, v15, s19
	global_store_short_d16_hi v[12:13], v15, off offset:128
	v_bfe_u32 v15, v18, 16, 1
	v_add3_u32 v15, v18, v15, s19
	global_store_short_d16_hi v[12:13], v15, off offset:256
	v_bfe_u32 v15, v19, 16, 1
	v_add3_u32 v15, v19, v15, s19
	global_store_short_d16_hi v[12:13], v15, off offset:384
	v_or_b32_e32 v12, s5, v9
	v_mad_u64_u32 v[12:13], s[6:7], v12, s84, v[8:9]
	ds_read_b128 v[16:19], v12 offset:9216
	ds_read_b128 v[20:23], v12 offset:9280
	s_waitcnt lgkmcnt(1)
	v_mfma_f32_16x16x32_bf16 v[16:19], v[16:19], v[0:3], 0
	v_or_b32_e32 v12, s5, v24
	v_lshl_or_b32 v12, v12, 6, v11
	s_or_b32 s6, s4, 48
	s_waitcnt lgkmcnt(0)
	v_mfma_f32_16x16x32_bf16 v[16:19], v[20:23], v[4:7], v[16:19]
	s_cmpk_gt_u32 s27, 0xff
	s_nop 6
	v_bfe_u32 v13, v16, 16, 1
	v_add3_u32 v15, v16, v13, s19
	v_ashrrev_i32_e32 v13, 31, v12
	v_lshl_add_u64 v[12:13], v[12:13], 1, s[16:17]
	global_store_short_d16_hi v[12:13], v15, off
	v_bfe_u32 v15, v17, 16, 1
	v_add3_u32 v15, v17, v15, s19
	global_store_short_d16_hi v[12:13], v15, off offset:128
	v_bfe_u32 v15, v18, 16, 1
	v_add3_u32 v15, v18, v15, s19
	global_store_short_d16_hi v[12:13], v15, off offset:256
	v_bfe_u32 v15, v19, 16, 1
	v_add3_u32 v15, v19, v15, s19
	global_store_short_d16_hi v[12:13], v15, off offset:384
	v_or_b32_e32 v12, s6, v9
	v_mad_u64_u32 v[12:13], s[4:5], v12, s84, v[8:9]
	ds_read_b128 v[16:19], v12 offset:9216
	ds_read_b128 v[20:23], v12 offset:9280
	s_waitcnt lgkmcnt(1)
	v_mfma_f32_16x16x32_bf16 v[16:19], v[16:19], v[0:3], 0
	v_or_b32_e32 v8, s6, v24
	s_waitcnt lgkmcnt(0)
	v_mfma_f32_16x16x32_bf16 v[16:19], v[20:23], v[4:7], v[16:19]
	s_nop 7
	v_bfe_u32 v12, v16, 16, 1
	v_add3_u32 v15, v16, v12, s19
	v_lshl_or_b32 v12, v8, 6, v11
	v_ashrrev_i32_e32 v13, 31, v12
	v_bfe_u32 v8, v17, 16, 1
	v_lshl_add_u64 v[12:13], v[12:13], 1, s[16:17]
	v_add3_u32 v8, v17, v8, s19
	global_store_short_d16_hi v[12:13], v8, off offset:128
	v_bfe_u32 v8, v18, 16, 1
	v_add3_u32 v8, v18, v8, s19
	global_store_short_d16_hi v[12:13], v8, off offset:256
	v_bfe_u32 v8, v19, 16, 1
	v_add3_u32 v8, v19, v8, s19
	global_store_short_d16_hi v[12:13], v15, off
	global_store_short_d16_hi v[12:13], v8, off offset:384
	s_cbranch_scc1 .LBB0_287
	v_lshlrev_b32_e32 v8, 3, v10
	v_mul_u32_u24_e32 v9, 0x90, v9
	v_lshlrev_b32_e32 v8, 1, v8
	v_add3_u32 v8, 0, v9, v8
	ds_read_b128 v[16:19], v8 offset:27648
	v_cmp_gt_u32_e32 vcc, 16, v14
	s_waitcnt lgkmcnt(0)
	v_mfma_f32_16x16x32_bf16 v[0:3], v[16:19], v[0:3], 0
	ds_read_b128 v[16:19], v8 offset:27712
	s_waitcnt lgkmcnt(0)
	v_mfma_f32_16x16x32_bf16 v[0:3], v[16:19], v[4:7], v[0:3]
	s_and_saveexec_b64 s[4:5], vcc
	s_cbranch_execz .LBB0_286
	s_nop 5
	v_bfe_u32 v1, v0, 16, 1
	s_movk_i32 s6, 0x7fff
	v_add3_u32 v2, v0, v1, s6
	v_lshlrev_b32_e32 v0, 1, v11
	v_mov_b32_e32 v1, v172
	v_lshl_add_u64 v[0:1], s[16:17], 0, v[0:1]
	v_add_co_u32_e32 v0, vcc, 0x4000, v0
	s_nop 1
	v_addc_co_u32_e32 v1, vcc, 0, v1, vcc
	global_store_short_d16_hi v[0:1], v2, off
	s_branch .LBB0_286
